# POST gMLP loop: bias vectors also loaded up front, mid-iteration full drains replaced by one counted wait
# baseline (speedup 1.0000x reference)
; __device__ __forceinline__ unsigned short f2bf(float f) { return (unsigned short)(pk2(f, 0.f) & 0xffffu); }
; __device__ __forceinline__ float bf2f(unsigned short h) { return __uint_as_float(((unsigned)h) << 16); }
; __device__ __forceinline__ float gelu_t(float x) { const float t = x * (-2.3022082f + -0.10294324f * x * x); return x * __builtin_amdgcn_rcpf(1.0f + __builtin_amdgcn_exp2f(t)); }
; __device__ __forceinline__ void post_phase(const Params& p, int l, LAS unsigned char* lds, int tid) {
;     ...
;                 for (int pb = 0; pb < 4; ++pb) {
;                     unsigned short uu[16];
; #pragma unroll
;                     for (int e = 0; e < 16; ++e) uu[e] = px[(size_t)(pb * 32 + (e & 3) + 8 * (e >> 2) + 4 * hi) * NIN + 1280 + col];
;                     f32x16 acc;
; #pragma unroll
;                     for (int e = 0; e < 16; ++e) acc[e] = 0.f;
; #pragma unroll
;                     for (int s = 0; s < 8; ++s) {
;                         const bf16x8 a = *(const bf16x8*)(wsb + (size_t)(pb * 32 + r32) * 128 + 16 * s + 8 * hi);
;                         acc = __builtin_amdgcn_mfma_f32_32x32x16_bf16(a, bfr[s], acc, 0, 0, 0);
;                     }
; #pragma unroll
;                     for (int e = 0; e < 16; ++e) {
;                         const int pp = pb * 32 + (e & 3) + 8 * (e >> 2) + 4 * hi;
;                         MIX[(size_t)(R0 + pp) * KOUT + 768 + col] = f2bf(gelu_t(bf2f(uu[e])) * (acc[e] + bs[pp]));
;                     }
.LBB0_358:
	v_lshl_add_u64 v[208:209], v[86:87], 0, s[0:1]
	v_lshl_add_u64 v[102:103], s[88:89], 0, v[100:101]
	global_load_dwordx4 v[192:195], v[208:209], off
	global_load_dwordx4 v[196:199], v[208:209], off offset:32
	global_load_dwordx4 v[200:203], v[208:209], off offset:64
	global_load_dwordx4 v[204:207], v[208:209], off offset:96
	global_load_dwordx4 v[0:3], v[102:103], off offset:-128
	global_load_dwordx4 v[136:139], v[102:103], off offset:-96
	global_load_dwordx4 v[160:163], v[102:103], off offset:-64
	global_load_dwordx4 v[164:167], v[102:103], off offset:-32
	global_load_dwordx4 v[168:171], v[102:103], off
	global_load_dwordx4 v[172:175], v[102:103], off offset:32
	global_load_dwordx4 v[176:179], v[102:103], off offset:64
	global_load_dwordx4 v[180:183], v[102:103], off offset:96
	v_lshl_add_u64 v[104:105], s[88:89], 0, v[90:91]
	s_brev_b32 s4, 48
	v_lshl_add_u64 v[150:151], s[88:89], 0, v[98:99]
	v_lshl_add_u64 v[100:101], v[100:101], 0, s[80:81]
	v_lshl_add_u64 v[98:99], v[98:99], 0, s[96:97]
	s_waitcnt vmcnt(7) lgkmcnt(7)
	v_mfma_f32_32x32x16_bf16 v[0:15], v[0:3], v[16:19], 0
	s_waitcnt vmcnt(6) lgkmcnt(6)
	v_mfma_f32_32x32x16_bf16 v[0:15], v[136:139], v[20:23], v[0:15]
	s_waitcnt vmcnt(5) lgkmcnt(5)
	v_mfma_f32_32x32x16_bf16 v[0:15], v[160:163], v[24:27], v[0:15]
	s_waitcnt vmcnt(4) lgkmcnt(4)
	v_mfma_f32_32x32x16_bf16 v[0:15], v[164:167], v[28:31], v[0:15]
	s_waitcnt vmcnt(3) lgkmcnt(3)
	v_mfma_f32_32x32x16_bf16 v[0:15], v[168:171], v[32:35], v[0:15]
	s_waitcnt vmcnt(2) lgkmcnt(2)
	v_mfma_f32_32x32x16_bf16 v[0:15], v[172:175], v[36:39], v[0:15]
	s_waitcnt vmcnt(1) lgkmcnt(1)
	v_mfma_f32_32x32x16_bf16 v[0:15], v[176:179], v[40:43], v[0:15]
	v_add_co_u32_e32 v102, vcc, s4, v104
	s_mov_b32 s4, 0xc001000
	s_nop 0
	v_addc_co_u32_e32 v103, vcc, 0, v105, vcc
	global_load_ushort v89, v[102:103], off offset:2560
	v_add_co_u32_e32 v152, vcc, s22, v150
	s_waitcnt vmcnt(1) lgkmcnt(0)
	v_mfma_f32_32x32x16_bf16 v[0:15], v[180:183], v[44:47], v[0:15]
	v_addc_co_u32_e32 v153, vcc, 0, v151, vcc
	s_waitcnt vmcnt(0)
	v_lshlrev_b32_e32 v89, 16, v89
	v_mul_f32_e32 v102, 0x3dd2d3e8, v89
	v_fma_f32 v102, -v102, v89, s21
	v_mul_f32_e32 v102, v102, v89
	v_exp_f32_e32 v102, v102
	v_add_co_u32_e32 v136, vcc, s4, v104
	s_mov_b32 s4, 0xc002000
	v_add_f32_e32 v102, 1.0, v102
	v_rcp_f32_e32 v102, v102
	v_addc_co_u32_e32 v137, vcc, 0, v105, vcc
	v_mul_f32_e32 v89, v102, v89
	v_mov_b32_e32 v146, v192
	v_mov_b32_e32 v147, v193
	v_mov_b32_e32 v148, v194
	v_mov_b32_e32 v149, v195
	v_add_f32_e32 v0, v0, v146
	global_load_ushort v146, v[136:137], off offset:2048
	v_add_co_u32_e32 v136, vcc, s4, v104
	s_mov_b32 s4, 0xc003000
	s_nop 0
	v_addc_co_u32_e32 v137, vcc, 0, v105, vcc
	global_load_ushort v156, v[136:137], off offset:1536
	v_add_co_u32_e32 v136, vcc, s4, v104
	s_mov_b32 s4, 0xc007000
	s_nop 0
	v_addc_co_u32_e32 v137, vcc, 0, v105, vcc
	global_load_ushort v157, v[136:137], off offset:1024
	v_add_co_u32_e32 v136, vcc, s4, v104
	s_mov_b32 s4, 0xc008000
	s_nop 0
	v_addc_co_u32_e32 v137, vcc, 0, v105, vcc
	global_load_ushort v158, v[136:137], off offset:2560
	v_add_co_u32_e32 v136, vcc, s4, v104
	s_mov_b32 s4, 0xc009000
	s_nop 0
	v_addc_co_u32_e32 v137, vcc, 0, v105, vcc
	global_load_ushort v145, v[136:137], off offset:2048
	v_add_co_u32_e32 v136, vcc, s4, v104
	s_mov_b32 s4, 0xc00a000
	s_nop 0
	v_addc_co_u32_e32 v137, vcc, 0, v105, vcc
	global_load_ushort v143, v[136:137], off offset:1536
	v_add_co_u32_e32 v136, vcc, s4, v104
	s_mov_b32 s4, 0xc00e000
	s_nop 0
	v_addc_co_u32_e32 v137, vcc, 0, v105, vcc
	global_load_ushort v142, v[136:137], off offset:1024
	v_add_co_u32_e32 v136, vcc, s4, v104
	s_mov_b32 s4, 0xc00f000
	s_nop 0
	v_addc_co_u32_e32 v137, vcc, 0, v105, vcc
	global_load_ushort v141, v[136:137], off offset:2560
	v_add_co_u32_e32 v136, vcc, s4, v104
	s_mov_b32 s4, 0xc010000
	s_nop 0
	v_addc_co_u32_e32 v137, vcc, 0, v105, vcc
	global_load_ushort v140, v[136:137], off offset:2048
	v_add_co_u32_e32 v136, vcc, s4, v104
	s_mov_b32 s4, 0xc011000
	s_nop 0
	v_addc_co_u32_e32 v137, vcc, 0, v105, vcc
	global_load_ushort v139, v[136:137], off offset:1536
	v_add_co_u32_e32 v136, vcc, s4, v104
	s_mov_b32 s4, 0xc015000
	s_nop 0
	v_addc_co_u32_e32 v137, vcc, 0, v105, vcc
	global_load_ushort v138, v[136:137], off offset:1024
	v_add_co_u32_e32 v136, vcc, s4, v104
	s_mov_b32 s4, 0xc016000
	s_nop 0
	v_addc_co_u32_e32 v137, vcc, 0, v105, vcc
	v_add_co_u32_e32 v154, vcc, s4, v104
	s_mov_b32 s4, 0xc017000
	s_nop 0
	v_addc_co_u32_e32 v155, vcc, 0, v105, vcc
	global_load_ushort v137, v[136:137], off offset:2560
	v_mul_f32_e32 v0, v89, v0
	global_load_ushort v136, v[154:155], off offset:2048
	v_add_co_u32_e32 v154, vcc, s4, v104
	s_mov_b32 s4, 0xc018000
	s_nop 0
	v_addc_co_u32_e32 v155, vcc, 0, v105, vcc
	v_add_co_u32_e32 v104, vcc, s4, v104
	v_cvt_pk_bf16_f32 v0, v0, s0
	s_nop 0
	v_addc_co_u32_e32 v105, vcc, 0, v105, vcc
	global_load_ushort v135, v[154:155], off offset:1536
	global_load_ushort v89, v[104:105], off offset:1024
	v_add_f32_e32 v1, v1, v147
	global_store_short v[152:153], v0, off offset:1536
	s_waitcnt vmcnt(15)
	v_lshlrev_b32_e32 v0, 16, v146
	v_mul_f32_e32 v104, 0x3dd2d3e8, v0
	v_fma_f32 v104, -v104, v0, s21
	v_mul_f32_e32 v104, v104, v0
	v_exp_f32_e32 v104, v104
	v_add_f32_e32 v3, v3, v149
	s_mov_b64 s[4:5], 0x1c000
	v_lshl_add_u64 v[90:91], v[90:91], 0, s[4:5]
	v_add_f32_e32 v104, 1.0, v104
	v_rcp_f32_e32 v104, v104
	s_nop 0
	v_mul_f32_e32 v0, v104, v0
	v_mul_f32_e32 v0, v0, v1
	v_cvt_pk_bf16_f32 v0, v0, s0
	global_store_short v[152:153], v0, off offset:3584
	s_waitcnt vmcnt(15)
; __device__ __forceinline__ unsigned short f2bf(float f) { return (unsigned short)(pk2(f, 0.f) & 0xffffu); }
; __device__ __forceinline__ float bf2f(unsigned short h) { return __uint_as_float(((unsigned)h) << 16); }
; __device__ __forceinline__ float gelu_t(float x) { const float t = x * (-2.3022082f + -0.10294324f * x * x); return x * __builtin_amdgcn_rcpf(1.0f + __builtin_amdgcn_exp2f(t)); }
; __device__ __forceinline__ void post_phase(const Params& p, int l, LAS unsigned char* lds, int tid) {
;     ...
;                 for (int pb = 0; pb < 4; ++pb) {
;                     unsigned short uu[16];
; #pragma unroll
;                     for (int e = 0; e < 16; ++e) uu[e] = px[(size_t)(pb * 32 + (e & 3) + 8 * (e >> 2) + 4 * hi) * NIN + 1280 + col];
;                     f32x16 acc;
; #pragma unroll
;                     for (int e = 0; e < 16; ++e) acc[e] = 0.f;
; #pragma unroll
;                     for (int s = 0; s < 8; ++s) {
;                         const bf16x8 a = *(const bf16x8*)(wsb + (size_t)(pb * 32 + r32) * 128 + 16 * s + 8 * hi);
;                         acc = __builtin_amdgcn_mfma_f32_32x32x16_bf16(a, bfr[s], acc, 0, 0, 0);
;                     }
; #pragma unroll
;                     for (int e = 0; e < 16; ++e) {
;                         const int pp = pb * 32 + (e & 3) + 8 * (e >> 2) + 4 * hi;
;                         MIX[(size_t)(R0 + pp) * KOUT + 768 + col] = f2bf(gelu_t(bf2f(uu[e])) * (acc[e] + bs[pp]));
;                     }
;                 }
;             }
;             __syncthreads();
	v_lshlrev_b32_e32 v0, 16, v156
	v_mul_f32_e32 v1, 0x3dd2d3e8, v0
	v_fma_f32 v1, -v1, v0, s21
	v_mul_f32_e32 v1, v1, v0
	v_exp_f32_e32 v1, v1
	s_nop 0
	v_add_f32_e32 v1, 1.0, v1
	v_rcp_f32_e32 v1, v1
	s_nop 0
	v_mul_f32_e32 v0, v1, v0
	v_add_f32_e32 v1, v2, v148
	v_mul_f32_e32 v0, v0, v1
	v_cvt_pk_bf16_f32 v2, v0, s0
	v_add_co_u32_e32 v0, vcc, s23, v150
	s_nop 1
	v_addc_co_u32_e32 v1, vcc, 0, v151, vcc
	global_store_short v[0:1], v2, off offset:1536
	s_waitcnt vmcnt(15)
	v_lshlrev_b32_e32 v2, 16, v157
	v_mul_f32_e32 v104, 0x3dd2d3e8, v2
	v_fma_f32 v104, -v104, v2, s21
	v_mul_f32_e32 v104, v104, v2
	v_exp_f32_e32 v104, v104
	s_nop 0
	v_add_f32_e32 v104, 1.0, v104
	v_rcp_f32_e32 v104, v104
	s_nop 0
	v_mul_f32_e32 v2, v104, v2
	v_mul_f32_e32 v2, v2, v3
	v_cvt_pk_bf16_f32 v2, v2, s0
	global_store_short v[0:1], v2, off offset:3584
	s_waitcnt vmcnt(15)
	v_lshlrev_b32_e32 v0, 16, v158
	v_mul_f32_e32 v1, 0x3dd2d3e8, v0
	v_fma_f32 v1, -v1, v0, s21
	v_mul_f32_e32 v1, v1, v0
	v_exp_f32_e32 v1, v1
	s_nop 0
	v_add_f32_e32 v1, 1.0, v1
	v_rcp_f32_e32 v1, v1
	s_nop 0
	v_mul_f32_e32 v104, v1, v0
	s_waitcnt vmcnt(4)
	v_mov_b32_e32 v0, v196
	v_mov_b32_e32 v1, v197
	v_mov_b32_e32 v2, v198
	v_mov_b32_e32 v3, v199
	v_add_f32_e32 v0, v4, v0
	v_mul_f32_e32 v0, v104, v0
	v_lshl_add_u64 v[104:105], s[88:89], 0, v[96:97]
	v_add_co_u32_e32 v146, vcc, s22, v104
	v_cvt_pk_bf16_f32 v0, v0, s0
	s_nop 0
	v_addc_co_u32_e32 v147, vcc, 0, v105, vcc
	global_store_short v[146:147], v0, off offset:1536
	v_lshlrev_b32_e32 v0, 16, v145
	v_mul_f32_e32 v4, 0x3dd2d3e8, v0
	v_fma_f32 v4, -v4, v0, s21
	v_mul_f32_e32 v4, v4, v0
	v_exp_f32_e32 v4, v4
	v_add_f32_e32 v1, v5, v1
	v_add_f32_e32 v3, v7, v3
	v_lshl_add_u64 v[96:97], v[96:97], 0, s[96:97]
	v_add_f32_e32 v4, 1.0, v4
	v_rcp_f32_e32 v4, v4
	s_nop 0
	v_mul_f32_e32 v0, v4, v0
	v_mul_f32_e32 v0, v0, v1
	v_cvt_pk_bf16_f32 v0, v0, s0
	global_store_short v[146:147], v0, off offset:3584
	v_lshlrev_b32_e32 v0, 16, v143
	v_mul_f32_e32 v1, 0x3dd2d3e8, v0
	v_fma_f32 v1, -v1, v0, s21
	v_mul_f32_e32 v1, v1, v0
	v_exp_f32_e32 v1, v1
	s_nop 0
	v_add_f32_e32 v1, 1.0, v1
	v_rcp_f32_e32 v1, v1
	s_nop 0
	v_mul_f32_e32 v0, v1, v0
	v_add_f32_e32 v1, v6, v2
	v_mul_f32_e32 v0, v0, v1
	v_cvt_pk_bf16_f32 v2, v0, s0
	v_add_co_u32_e32 v0, vcc, s23, v104
	s_nop 1
	v_addc_co_u32_e32 v1, vcc, 0, v105, vcc
	global_store_short v[0:1], v2, off offset:1536
	v_lshlrev_b32_e32 v2, 16, v142
	v_mul_f32_e32 v4, 0x3dd2d3e8, v2
	v_fma_f32 v4, -v4, v2, s21
	v_mul_f32_e32 v4, v4, v2
	v_exp_f32_e32 v4, v4
	s_nop 0
	v_add_f32_e32 v4, 1.0, v4
	v_rcp_f32_e32 v4, v4
	s_nop 0
	v_mul_f32_e32 v2, v4, v2
	v_mul_f32_e32 v2, v2, v3
	v_cvt_pk_bf16_f32 v2, v2, s0
	global_store_short v[0:1], v2, off offset:3584
	v_lshlrev_b32_e32 v0, 16, v141
	v_mul_f32_e32 v1, 0x3dd2d3e8, v0
	v_fma_f32 v1, -v1, v0, s21
	v_mul_f32_e32 v1, v1, v0
	v_exp_f32_e32 v1, v1
	s_nop 0
	v_add_f32_e32 v1, 1.0, v1
	v_rcp_f32_e32 v1, v1
	s_nop 0
	v_mul_f32_e32 v4, v1, v0
	v_mov_b32_e32 v0, v200
	v_mov_b32_e32 v1, v201
	v_mov_b32_e32 v2, v202
	v_mov_b32_e32 v3, v203
	v_add_f32_e32 v0, v8, v0
	v_mul_f32_e32 v0, v4, v0
	v_lshl_add_u64 v[4:5], s[88:89], 0, v[94:95]
	v_add_co_u32_e32 v6, vcc, s22, v4
	v_cvt_pk_bf16_f32 v0, v0, s0
	s_nop 0
	v_addc_co_u32_e32 v7, vcc, 0, v5, vcc
	global_store_short v[6:7], v0, off offset:1536
	v_lshlrev_b32_e32 v0, 16, v140
	v_mul_f32_e32 v8, 0x3dd2d3e8, v0
	v_fma_f32 v8, -v8, v0, s21
	v_mul_f32_e32 v8, v8, v0
	v_exp_f32_e32 v8, v8
	v_add_f32_e32 v1, v9, v1
	v_add_f32_e32 v3, v11, v3
	v_lshl_add_u64 v[94:95], v[94:95], 0, s[96:97]
	v_add_f32_e32 v8, 1.0, v8
	v_rcp_f32_e32 v8, v8
	s_nop 0
	v_mul_f32_e32 v0, v8, v0
	v_mul_f32_e32 v0, v0, v1
	v_cvt_pk_bf16_f32 v0, v0, s0
	global_store_short v[6:7], v0, off offset:3584
	v_lshlrev_b32_e32 v0, 16, v139
	v_mul_f32_e32 v1, 0x3dd2d3e8, v0
	v_fma_f32 v1, -v1, v0, s21
	v_mul_f32_e32 v1, v1, v0
	v_exp_f32_e32 v1, v1
	s_nop 0
	v_add_f32_e32 v1, 1.0, v1
	v_rcp_f32_e32 v1, v1
	s_nop 0
	v_mul_f32_e32 v0, v1, v0
	v_add_f32_e32 v1, v10, v2
	v_mul_f32_e32 v0, v0, v1
	v_cvt_pk_bf16_f32 v2, v0, s0
	v_add_co_u32_e32 v0, vcc, s23, v4
	s_nop 1
	v_addc_co_u32_e32 v1, vcc, 0, v5, vcc
	global_store_short v[0:1], v2, off offset:1536
	v_lshlrev_b32_e32 v2, 16, v138
	v_mul_f32_e32 v4, 0x3dd2d3e8, v2
	v_fma_f32 v4, -v4, v2, s21
	v_mul_f32_e32 v4, v4, v2
	v_exp_f32_e32 v4, v4
	s_nop 0
	v_add_f32_e32 v4, 1.0, v4
	v_rcp_f32_e32 v4, v4
	s_nop 0
	v_mul_f32_e32 v2, v4, v2
	v_mul_f32_e32 v2, v2, v3
	v_cvt_pk_bf16_f32 v2, v2, s0
	global_store_short v[0:1], v2, off offset:3584
	v_lshlrev_b32_e32 v0, 16, v137
	v_mul_f32_e32 v1, 0x3dd2d3e8, v0
	v_fma_f32 v1, -v1, v0, s21
	v_mul_f32_e32 v1, v1, v0
	v_exp_f32_e32 v1, v1
	s_nop 0
	v_add_f32_e32 v1, 1.0, v1
	v_rcp_f32_e32 v1, v1
	s_nop 0
	v_mul_f32_e32 v4, v1, v0
	v_mov_b32_e32 v0, v204
	v_mov_b32_e32 v1, v205
	v_mov_b32_e32 v2, v206
	v_mov_b32_e32 v3, v207
	v_add_f32_e32 v0, v12, v0
	v_mul_f32_e32 v0, v4, v0
	v_lshl_add_u64 v[4:5], s[88:89], 0, v[92:93]
	v_add_co_u32_e32 v6, vcc, s22, v4
	v_cvt_pk_bf16_f32 v0, v0, s0
	s_nop 0
	v_addc_co_u32_e32 v7, vcc, 0, v5, vcc
	global_store_short v[6:7], v0, off offset:1536
	v_lshlrev_b32_e32 v0, 16, v136
	v_mul_f32_e32 v8, 0x3dd2d3e8, v0
	v_fma_f32 v8, -v8, v0, s21
	v_mul_f32_e32 v8, v8, v0
	v_exp_f32_e32 v8, v8
	v_add_f32_e32 v1, v13, v1
	v_add_f32_e32 v3, v15, v3
	v_lshl_add_u64 v[92:93], v[92:93], 0, s[96:97]
	v_add_f32_e32 v8, 1.0, v8
	v_rcp_f32_e32 v8, v8
	s_nop 0
	v_mul_f32_e32 v0, v8, v0
	v_mul_f32_e32 v0, v0, v1
	v_cvt_pk_bf16_f32 v0, v0, s0
	global_store_short v[6:7], v0, off offset:3584
	v_lshlrev_b32_e32 v0, 16, v135
	v_mul_f32_e32 v1, 0x3dd2d3e8, v0
	v_fma_f32 v1, -v1, v0, s21
	v_mul_f32_e32 v1, v1, v0
	v_exp_f32_e32 v1, v1
	s_nop 0
	v_add_f32_e32 v1, 1.0, v1
	v_rcp_f32_e32 v1, v1
	s_nop 0
	v_mul_f32_e32 v0, v1, v0
	v_add_f32_e32 v1, v14, v2
	v_mul_f32_e32 v0, v0, v1
	v_cvt_pk_bf16_f32 v2, v0, s0
	v_add_co_u32_e32 v0, vcc, s23, v4
	s_nop 1
	v_addc_co_u32_e32 v1, vcc, 0, v5, vcc
	global_store_short v[0:1], v2, off offset:1536
	v_lshlrev_b32_e32 v2, 16, v89
	v_mul_f32_e32 v4, 0x3dd2d3e8, v2
	v_fma_f32 v4, -v4, v2, s21
	v_mul_f32_e32 v4, v4, v2
	v_exp_f32_e32 v4, v4
	s_nop 0
	v_add_f32_e32 v4, 1.0, v4
	v_rcp_f32_e32 v4, v4
	s_nop 0
	v_mul_f32_e32 v2, v4, v2
	v_mul_f32_e32 v2, v2, v3
	v_cvt_pk_bf16_f32 v2, v2, s0
	s_add_u32 s0, s0, 0x80
	s_addc_u32 s1, s1, 0
	s_cmpk_eq_i32 s0, 0x200
	global_store_short v[0:1], v2, off offset:3584
	s_cbranch_scc0 .LBB0_358
	v_readlane_b32 s42, v253, 24
	s_mov_b64 s[0:1], 0
	v_readlane_b32 s43, v253, 25
	s_barrier
